# grid barrier: XCD leaders no longer republish the generation (nobody polls it)
# baseline (speedup 1.0000x reference)
; __device__ __forceinline__ unsigned xb_add(unsigned* p, unsigned v) { return __hip_atomic_fetch_add(p, v, __ATOMIC_RELAXED, __HIP_MEMORY_SCOPE_AGENT); }
; __device__ __forceinline__ void xcd_barrier(const XcdBarrier& b) {
;     ...
;             __builtin_amdgcn_fence(__ATOMIC_ACQUIRE, "agent");
;             xb_add(&bar[XB_XGEN(b.x)], 1u);
;             asm volatile("s_waitcnt vmcnt(0)" ::: "memory");
.LBB0_389:
	s_or_b64 exec, exec, s[8:9]
	s_mov_b64 s[8:9], exec
	v_mbcnt_lo_u32_b32 v2, s8, 0
	v_mbcnt_hi_u32_b32 v2, s9, v2
	v_cmp_eq_u32_e32 vcc, 0, v2
	s_waitcnt vmcnt(0)
	buffer_inv sc1
	s_and_saveexec_b64 s[10:11], vcc
	s_cbranch_execz .LBB0_391
	s_bcnt1_i32_b64 s3, s[8:9]
	v_mov_b32_e32 v2, 0x2000
	v_mov_b32_e32 v3, s3
.LBB0_391:
	s_or_b64 exec, exec, s[10:11]
	s_waitcnt vmcnt(0)

; __device__ __forceinline__ unsigned xb_add(unsigned* p, unsigned v) { return __hip_atomic_fetch_add(p, v, __ATOMIC_RELAXED, __HIP_MEMORY_SCOPE_AGENT); }
; __device__ __forceinline__ void xcd_barrier(const XcdBarrier& b) {
;     ...
;             __builtin_amdgcn_fence(__ATOMIC_ACQUIRE, "agent");
;             xb_add(&bar[XB_XGEN(b.x)], 1u);
;             asm volatile("s_waitcnt vmcnt(0)" ::: "memory");
.LBB0_614:
	s_or_b64 exec, exec, s[8:9]
	s_mov_b64 s[8:9], exec
	v_mbcnt_lo_u32_b32 v2, s8, 0
	v_mbcnt_hi_u32_b32 v2, s9, v2
	v_cmp_eq_u32_e32 vcc, 0, v2
	s_waitcnt vmcnt(0)
	buffer_inv sc1
	s_and_saveexec_b64 s[10:11], vcc
	s_cbranch_execz .LBB0_616
	s_bcnt1_i32_b64 s3, s[8:9]
	v_mov_b32_e32 v2, 0x2000
	v_mov_b32_e32 v3, s3
.LBB0_616:
	s_or_b64 exec, exec, s[10:11]
	s_waitcnt vmcnt(0)

; __device__ __forceinline__ unsigned xb_add(unsigned* p, unsigned v) { return __hip_atomic_fetch_add(p, v, __ATOMIC_RELAXED, __HIP_MEMORY_SCOPE_AGENT); }
; __device__ __forceinline__ void xcd_barrier(const XcdBarrier& b) {
;     ...
;             __builtin_amdgcn_fence(__ATOMIC_ACQUIRE, "agent");
;             xb_add(&bar[XB_XGEN(b.x)], 1u);
;             asm volatile("s_waitcnt vmcnt(0)" ::: "memory");
.LBB0_753:
	s_or_b64 exec, exec, s[8:9]
	s_mov_b64 s[8:9], exec
	v_mbcnt_lo_u32_b32 v2, s8, 0
	v_mbcnt_hi_u32_b32 v2, s9, v2
	v_cmp_eq_u32_e32 vcc, 0, v2
	s_waitcnt vmcnt(0)
	buffer_inv sc1
	s_and_saveexec_b64 s[10:11], vcc
	s_cbranch_execz .LBB0_755
	s_bcnt1_i32_b64 s2, s[8:9]
	v_mov_b32_e32 v2, 0x2000
	v_mov_b32_e32 v3, s2
.LBB0_755:
	s_or_b64 exec, exec, s[10:11]
	s_waitcnt vmcnt(0)
